# ph0 GEMV: next trip's 8 weight rows prefetched into a second register set, handed over at the trip end
# baseline (speedup 1.0000x reference)
; __device__ __forceinline__ void ph_mods(const TI ti, CArgs& a, unsigned char* ldsg) {
;     ...
;     for (int item = ti.bid; item < DEPTH * 96; item += ti.nblk) {
;         const int l = item / 96, n0 = (item % 96) * 64;
;         const float* W = a.in[4] + (size_t)l * 1024 * 6144 + n0 + lane;
;         float acc[9];
; #pragma unroll
;         for (int r = 0; r < 9; ++r) acc[r] = 0.f;
; #pragma unroll 8
;         for (int k = w * 128; k < w * 128 + 128; ++k) {
;             const float wv = W[(size_t)k * 6144];
; #pragma unroll
;             for (int r = 0; r < 9; ++r) acc[r] += sc[r * 1024 + k] * wv;
;         }
.LBB0_922:
	s_mul_hi_i32 s3, s1, 0x2aaaaaab
	s_lshr_b32 s4, s3, 31
	s_ashr_i32 s3, s3, 4
	s_add_i32 s3, s3, s4
	s_mul_i32 s4, s3, 0x60
	s_sub_i32 s4, s1, s4
	s_lshl_b32 s44, s4, 6
	s_ashr_i32 s45, s44, 31
	s_mul_i32 s7, s3, 0x1800000
	s_lshl_b64 s[4:5], s[44:45], 2
	s_mul_hi_i32 s6, s3, 0x1800000
	s_add_u32 s4, s7, s4
	s_addc_u32 s5, s6, s5
	v_mov_b32_e32 v16, 0
	v_lshl_add_u64 v[10:11], v[8:9], 0, s[4:5]
	s_mov_b64 s[46:47], 0
	v_mov_b32_e32 v25, v23
	v_mov_b32_e32 v17, v16
	v_mov_b32_e32 v18, v16
	v_mov_b32_e32 v19, v16
	v_mov_b32_e32 v14, v16
	v_mov_b32_e32 v15, v16
	v_mov_b32_e32 v12, v16
	v_mov_b32_e32 v13, v16
	v_mov_b32_e32 v26, v16
	s_mov_b64 s[98:99], 0x6000
	global_load_dword v70, v[10:11], off
	v_lshl_add_u64 v[86:87], v[10:11], 0, s[98:99]
	global_load_dword v72, v[86:87], off
	v_lshl_add_u64 v[88:89], v[86:87], 0, s[98:99]
	global_load_dword v74, v[88:89], off
	v_lshl_add_u64 v[86:87], v[88:89], 0, s[98:99]
	global_load_dword v76, v[86:87], off
	v_lshl_add_u64 v[88:89], v[86:87], 0, s[98:99]
	global_load_dword v78, v[88:89], off
	v_lshl_add_u64 v[86:87], v[88:89], 0, s[98:99]
	global_load_dword v80, v[86:87], off
	v_lshl_add_u64 v[88:89], v[86:87], 0, s[98:99]
	global_load_dword v82, v[88:89], off
	v_lshl_add_u64 v[86:87], v[88:89], 0, s[98:99]
	global_load_dword v84, v[86:87], off
.LBB0_923:
	v_lshl_add_u64 v[20:21], v[10:11], 0, s[46:47]
	s_cmp_eq_u32 s46, 0x2d0000
	s_cbranch_scc1 .Lph0_nopf
	s_mov_b64 s[98:99], 0x30000
	v_lshl_add_u64 v[106:107], v[20:21], 0, s[98:99]
	s_mov_b64 s[98:99], 0x6000
	global_load_dword v90, v[106:107], off
	v_lshl_add_u64 v[86:87], v[106:107], 0, s[98:99]
	global_load_dword v92, v[86:87], off
	v_lshl_add_u64 v[88:89], v[86:87], 0, s[98:99]
	global_load_dword v94, v[88:89], off
	v_lshl_add_u64 v[86:87], v[88:89], 0, s[98:99]
	global_load_dword v96, v[86:87], off
	v_lshl_add_u64 v[88:89], v[86:87], 0, s[98:99]
	global_load_dword v98, v[88:89], off
	v_lshl_add_u64 v[86:87], v[88:89], 0, s[98:99]
	global_load_dword v100, v[86:87], off
	v_lshl_add_u64 v[88:89], v[86:87], 0, s[98:99]
	global_load_dword v102, v[88:89], off
	v_lshl_add_u64 v[86:87], v[88:89], 0, s[98:99]
	global_load_dword v104, v[86:87], off
.Lph0_nopf:
	s_cmp_eq_u32 s46, 0x2d0000
	s_cbranch_scc1 .Lph0_w0
	s_waitcnt vmcnt(8)
	s_branch .Lph0_wd

; __device__ __forceinline__ void ph_mods(const TI ti, CArgs& a, unsigned char* ldsg) {
;     ...
; #pragma unroll 8
;         for (int k = w * 128; k < w * 128 + 128; ++k) {
;             const float wv = W[(size_t)k * 6144];
; #pragma unroll
;             for (int r = 0; r < 9; ++r) acc[r] += sc[r * 1024 + k] * wv;
;         }
; #pragma unroll
;         for (int r = 0; r < 9; ++r) part[(w * 9 + r) * 64 + lane] = acc[r];
;         __syncthreads();
;         for (int idx = tid; idx < 576; idx += 512) {
;             const int r = idx >> 6, ln = idx & 63; float s = a.in[5][l * 6144 + n0 + ln];
;             for (int ww = 0; ww < 8; ++ww) s += part[(ww * 9 + r) * 64 + ln];
;             MOD[((size_t)l * 9 + r) * 6144 + n0 + ln] = s;
.Lph0_wd:
	ds_read_b128 v[28:31], v25
	ds_read_b128 v[2:5], v25 offset:16
	ds_read_b128 v[32:35], v25 offset:4096
	v_add_co_u32_e64 v64, s[40:41], s65, v20
	s_waitcnt lgkmcnt(2)
	v_mov_b32_e32 v36, v28
	v_addc_co_u32_e64 v65, s[40:41], 0, v21, s[40:41]
	s_waitcnt lgkmcnt(0)
	v_mov_b32_e32 v37, v32
	v_add_co_u32_e64 v28, s[40:41], s71, v20
	v_mov_b32_e32 v32, v29
	s_nop 0
	v_addc_co_u32_e64 v29, s[40:41], 0, v21, s[40:41]
	s_mov_b32 s4, 0x12000
	s_add_u32 s46, s46, 0x30000
	s_addc_u32 s47, s47, 0
	s_cmp_eq_u32 s46, 0x300000
	v_pk_fma_f32 v[16:17], v[70:71], v[36:37], v[16:17] op_sel_hi:[0,1,1]
	ds_read_b128 v[36:39], v25 offset:8192
	ds_read_b128 v[40:43], v25 offset:12288
	s_waitcnt lgkmcnt(1)
	v_mov_b32_e32 v44, v36
	s_waitcnt lgkmcnt(0)
	v_mov_b32_e32 v45, v40
	v_pk_fma_f32 v[18:19], v[70:71], v[44:45], v[18:19] op_sel_hi:[0,1,1]
	ds_read_b128 v[44:47], v25 offset:16384
	ds_read_b128 v[48:51], v25 offset:20480
	v_mov_b32_e32 v40, v37
	s_waitcnt lgkmcnt(1)
	v_mov_b32_e32 v52, v44
	s_waitcnt lgkmcnt(0)
	v_mov_b32_e32 v53, v48
	v_pk_fma_f32 v[14:15], v[70:71], v[52:53], v[14:15] op_sel_hi:[0,1,1]
	ds_read_b128 v[52:55], v25 offset:24576
	ds_read_b128 v[56:59], v25 offset:28672
	v_mov_b32_e32 v48, v45
	s_waitcnt lgkmcnt(1)
	v_mov_b32_e32 v60, v52
	s_waitcnt lgkmcnt(0)
	v_mov_b32_e32 v61, v56
	v_pk_fma_f32 v[12:13], v[70:71], v[60:61], v[12:13] op_sel_hi:[0,1,1]
	ds_read_b128 v[60:63], v25 offset:32768
	v_mov_b32_e32 v56, v53
	s_waitcnt lgkmcnt(0)
	v_fmac_f32_e32 v26, v70, v60
	v_pk_fma_f32 v[16:17], v[72:73], v[32:33], v[16:17] op_sel_hi:[0,1,1]
	v_pk_fma_f32 v[18:19], v[72:73], v[40:41], v[18:19] op_sel_hi:[0,1,1]
	v_pk_fma_f32 v[14:15], v[72:73], v[48:49], v[14:15] op_sel_hi:[0,1,1]
	v_pk_fma_f32 v[12:13], v[72:73], v[56:57], v[12:13] op_sel_hi:[0,1,1]
	v_fmac_f32_e32 v26, v72, v61
	v_mov_b32_e32 v28, v30
	v_mov_b32_e32 v29, v34
	v_mov_b32_e32 v34, v31
	v_mov_b32_e32 v32, v2
	v_pk_fma_f32 v[16:17], v[74:75], v[28:29], v[16:17] op_sel_hi:[0,1,1]
	v_mov_b32_e32 v28, v38
	v_mov_b32_e32 v29, v42
	v_pk_fma_f32 v[28:29], v[74:75], v[28:29], v[18:19] op_sel_hi:[0,1,1]
	v_mov_b32_e32 v18, v46
	v_mov_b32_e32 v19, v50
	v_pk_fma_f32 v[14:15], v[74:75], v[18:19], v[14:15] op_sel_hi:[0,1,1]
	v_mov_b32_e32 v18, v54
	v_mov_b32_e32 v19, v58
	v_pk_fma_f32 v[12:13], v[74:75], v[18:19], v[12:13] op_sel_hi:[0,1,1]
	v_add_co_u32_e64 v18, s[40:41], s4, v20
	v_fmac_f32_e32 v26, v74, v62
	s_nop 0
	v_addc_co_u32_e64 v19, s[40:41], 0, v21, s[40:41]
	v_mov_b32_e32 v42, v39
	v_mov_b32_e32 v50, v47
	v_mov_b32_e32 v58, v55
	s_mov_b32 s4, 0x1e000
	v_pk_fma_f32 v[18:19], v[76:77], v[34:35], v[16:17] op_sel_hi:[0,1,1]
	v_pk_fma_f32 v[16:17], v[76:77], v[42:43], v[28:29] op_sel_hi:[0,1,1]
	v_add_co_u32_e64 v28, s[40:41], s69, v20
	v_pk_fma_f32 v[14:15], v[76:77], v[50:51], v[14:15] op_sel_hi:[0,1,1]
	s_nop 0
	v_addc_co_u32_e64 v29, s[40:41], 0, v21, s[40:41]
	v_pk_fma_f32 v[12:13], v[76:77], v[58:59], v[12:13] op_sel_hi:[0,1,1]
	v_fmac_f32_e32 v26, v76, v63
	ds_read_b128 v[28:31], v25 offset:4112
	v_add_co_u32_e64 v60, s[40:41], s4, v20
	s_mov_b32 s4, 0x24000
	s_nop 0
	v_addc_co_u32_e64 v61, s[40:41], 0, v21, s[40:41]
	s_waitcnt lgkmcnt(0)
	v_mov_b32_e32 v33, v28
	v_mov_b32_e32 v28, v3
	v_pk_fma_f32 v[18:19], v[78:79], v[32:33], v[18:19] op_sel_hi:[0,1,1]
	ds_read_b128 v[32:35], v25 offset:8208
	ds_read_b128 v[36:39], v25 offset:12304
	s_waitcnt lgkmcnt(1)
	v_mov_b32_e32 v40, v32
	s_waitcnt lgkmcnt(0)
	v_mov_b32_e32 v41, v36
	v_pk_fma_f32 v[16:17], v[78:79], v[40:41], v[16:17] op_sel_hi:[0,1,1]
	ds_read_b128 v[40:43], v25 offset:16400
	ds_read_b128 v[44:47], v25 offset:20496
	v_mov_b32_e32 v36, v33
	s_waitcnt lgkmcnt(1)
	v_mov_b32_e32 v48, v40
	s_waitcnt lgkmcnt(0)
	v_mov_b32_e32 v49, v44
	v_pk_fma_f32 v[14:15], v[78:79], v[48:49], v[14:15] op_sel_hi:[0,1,1]
	ds_read_b128 v[48:51], v25 offset:24592
	ds_read_b128 v[52:55], v25 offset:28688
	v_mov_b32_e32 v44, v41
	s_waitcnt lgkmcnt(1)
	v_mov_b32_e32 v56, v48
	s_waitcnt lgkmcnt(0)
	v_mov_b32_e32 v57, v52
	v_pk_fma_f32 v[12:13], v[78:79], v[56:57], v[12:13] op_sel_hi:[0,1,1]
	ds_read_b128 v[56:59], v25 offset:32784
	v_mov_b32_e32 v52, v49
	v_add_u32_e32 v25, 32, v25
	s_waitcnt lgkmcnt(0)
	v_fmac_f32_e32 v26, v78, v56
	v_pk_fma_f32 v[2:3], v[80:81], v[28:29], v[18:19] op_sel_hi:[0,1,1]
	v_add_co_u32_e64 v18, s[40:41], s4, v20
	v_pk_fma_f32 v[16:17], v[80:81], v[36:37], v[16:17] op_sel_hi:[0,1,1]
	s_nop 0
	v_addc_co_u32_e64 v19, s[40:41], 0, v21, s[40:41]
	v_pk_fma_f32 v[14:15], v[80:81], v[44:45], v[14:15] op_sel_hi:[0,1,1]
	v_pk_fma_f32 v[12:13], v[80:81], v[52:53], v[12:13] op_sel_hi:[0,1,1]
	v_fmac_f32_e32 v26, v80, v57
	v_mov_b32_e32 v18, v4
	v_mov_b32_e32 v19, v30
	s_mov_b32 s4, 0x2a000
	v_mov_b32_e32 v30, v5
	v_pk_fma_f32 v[2:3], v[82:83], v[18:19], v[2:3] op_sel_hi:[0,1,1]
	v_mov_b32_e32 v18, v34
	v_mov_b32_e32 v19, v38
	v_pk_fma_f32 v[18:19], v[82:83], v[18:19], v[16:17] op_sel_hi:[0,1,1]
	v_mov_b32_e32 v16, v42
	v_mov_b32_e32 v17, v46
	v_pk_fma_f32 v[14:15], v[82:83], v[16:17], v[14:15] op_sel_hi:[0,1,1]
	v_mov_b32_e32 v16, v50
	v_mov_b32_e32 v17, v54
	v_pk_fma_f32 v[12:13], v[82:83], v[16:17], v[12:13] op_sel_hi:[0,1,1]
	v_add_co_u32_e64 v16, s[40:41], s4, v20
	v_fmac_f32_e32 v26, v82, v58
	s_nop 0
	v_addc_co_u32_e64 v17, s[40:41], 0, v21, s[40:41]
	v_mov_b32_e32 v38, v35
	v_mov_b32_e32 v46, v43
	v_mov_b32_e32 v54, v51
	v_pk_fma_f32 v[16:17], v[84:85], v[30:31], v[2:3] op_sel_hi:[0,1,1]
	v_pk_fma_f32 v[18:19], v[84:85], v[38:39], v[18:19] op_sel_hi:[0,1,1]
	v_pk_fma_f32 v[14:15], v[84:85], v[46:47], v[14:15] op_sel_hi:[0,1,1]
	v_pk_fma_f32 v[12:13], v[84:85], v[54:55], v[12:13] op_sel_hi:[0,1,1]
	v_fmac_f32_e32 v26, v84, v59
	s_waitcnt vmcnt(0)
	v_mov_b32_e32 v70, v90
	v_mov_b32_e32 v72, v92
	v_mov_b32_e32 v74, v94
	v_mov_b32_e32 v76, v96
	v_mov_b32_e32 v78, v98
	v_mov_b32_e32 v80, v100
	v_mov_b32_e32 v82, v102
	v_mov_b32_e32 v84, v104
	s_cbranch_scc0 .LBB0_923
	ds_write2st64_b32 v24, v16, v17 offset0:144 offset1:145
	ds_write2st64_b32 v24, v18, v19 offset0:146 offset1:147
	ds_write2st64_b32 v24, v14, v15 offset0:148 offset1:149
	ds_write2st64_b32 v24, v12, v13 offset0:150 offset1:151
	ds_write_b32 v24, v26 offset:38912
	s_waitcnt lgkmcnt(0)
	s_barrier
	s_and_saveexec_b64 s[4:5], vcc
	s_cbranch_execz .LBB0_921
	s_mul_i32 s6, s3, 0x1800
	s_add_i32 s10, s6, s44
	v_or_b32_e32 v2, s10, v180
	v_ashrrev_i32_e32 v3, 31, v2
	s_mul_hi_i32 s7, s3, 9
	s_mul_i32 s6, s3, 9
	v_lshl_add_u64 v[2:3], v[2:3], 2, s[42:43]
	v_lshl_add_u64 v[4:5], s[44:45], 2, v[6:7]
	s_mov_b64 s[44:45], 0
	v_mov_b32_e32 v0, v178
